# attention tile loop: counted LDS waits extended through the last P*V block of each half (state carried across the rescale branch)
# speedup vs baseline: 1.1795x; 1.0046x over previous
.LBB0_425:
	ds_read_b64_tr_b16 v[202:203], v199 offset:0x600
	ds_read_b64_tr_b16 v[204:205], v199 offset:0xe00
	ds_read_b64_tr_b16 v[206:207], v199 offset:0x1600
	ds_read_b64_tr_b16 v[208:209], v199 offset:0x1e00
	ds_read_b64_tr_b16 v[210:211], v199 offset:0x2600
	ds_read_b64_tr_b16 v[212:213], v199 offset:0x2e00
	ds_read_b64_tr_b16 v[222:223], v199 offset:0x3600
	ds_read_b64_tr_b16 v[224:225], v199 offset:0x3e00
	s_add_i32 s4, s19, 1
	s_cmp_lg_u32 s19, 2
	s_cselect_b32 s18, s4, 0
	s_waitcnt lgkmcnt(6)
	v_mfma_f32_32x32x16_bf16 v[16:31], v[64:67], v[202:205], v[16:31]
	s_lshl_b32 s4, s18, 14
	s_add_i32 s17, s4, 16
	v_add_u32_e32 v64, s17, v184
	s_waitcnt vmcnt(4)
	s_waitcnt vmcnt(4)
	ds_write_b128 v64, v[132:135]
	v_add_u32_e32 v64, s17, v186
	ds_write_b128 v64, v[140:143]
	s_waitcnt lgkmcnt(6)
	v_mfma_f32_32x32x16_bf16 v[16:31], v[72:75], v[206:209], v[16:31]
	v_add_u32_e32 v64, s17, v183
	ds_write_b128 v64, v[128:131] offset:49152
	v_add_u32_e32 v64, s17, v188
	v_cmp_gt_f32_e32 vcc, 1.0, v200
	ds_write_b128 v64, v[136:139] offset:49152
	s_waitcnt lgkmcnt(6)
	v_mfma_f32_32x32x16_bf16 v[16:31], v[68:71], v[210:213], v[16:31]
	s_waitcnt lgkmcnt(4)
	v_mfma_f32_32x32x16_bf16 v[16:31], v[76:79], v[222:225], v[16:31]
	s_cbranch_vccz .LBB0_429
	s_and_saveexec_b64 s[4:5], s[0:1]
	ds_write_b32 v179, v200 offset:128
	s_or_b64 exec, exec, s[4:5]
	s_waitcnt lgkmcnt(0)
	v_add_u32_e32 v76, v177, v176
	ds_read_b128 v[64:67], v76 offset:224
	ds_read_b128 v[68:71], v76 offset:192
	ds_read_b128 v[72:75], v76 offset:160
	ds_read_b128 v[76:79], v76 offset:128
	s_waitcnt lgkmcnt(3)
	v_pk_mul_f32 v[12:13], v[12:13], v[64:65]
	s_waitcnt lgkmcnt(2)
	v_pk_mul_f32 v[8:9], v[8:9], v[68:69]
	s_waitcnt lgkmcnt(1)
	v_pk_mul_f32 v[4:5], v[4:5], v[72:73]
	v_pk_mul_f32 v[14:15], v[14:15], v[66:67]
	v_pk_mul_f32 v[10:11], v[10:11], v[70:71]
	v_pk_mul_f32 v[6:7], v[6:7], v[74:75]
	s_waitcnt lgkmcnt(0)
	v_pk_mul_f32 v[2:3], v[2:3], v[78:79]
	v_pk_mul_f32 v[0:1], v[0:1], v[76:77]
	v_pk_mul_f32 v[60:61], v[60:61], v[64:65]
	v_pk_mul_f32 v[56:57], v[56:57], v[68:69]
	v_pk_mul_f32 v[52:53], v[52:53], v[72:73]
	v_pk_mul_f32 v[62:63], v[62:63], v[66:67]
	v_pk_mul_f32 v[58:59], v[58:59], v[70:71]
	v_pk_mul_f32 v[54:55], v[54:55], v[74:75]
	v_pk_mul_f32 v[50:51], v[50:51], v[78:79]
	v_pk_mul_f32 v[48:49], v[48:49], v[76:77]
	v_pk_mul_f32 v[44:45], v[44:45], v[64:65]
	v_pk_mul_f32 v[40:41], v[40:41], v[68:69]
	v_pk_mul_f32 v[36:37], v[36:37], v[72:73]
	v_pk_mul_f32 v[46:47], v[46:47], v[66:67]
	v_pk_mul_f32 v[42:43], v[42:43], v[70:71]
	v_pk_mul_f32 v[38:39], v[38:39], v[74:75]
	v_pk_mul_f32 v[34:35], v[34:35], v[78:79]
	v_pk_mul_f32 v[32:33], v[32:33], v[76:77]
	v_pk_mul_f32 v[28:29], v[28:29], v[64:65]
	v_pk_mul_f32 v[24:25], v[24:25], v[68:69]
	v_pk_mul_f32 v[20:21], v[20:21], v[72:73]
	v_pk_mul_f32 v[30:31], v[30:31], v[66:67]
	v_pk_mul_f32 v[26:27], v[26:27], v[70:71]
	v_pk_mul_f32 v[22:23], v[22:23], v[74:75]
	v_pk_mul_f32 v[18:19], v[18:19], v[78:79]
	v_pk_mul_f32 v[16:17], v[16:17], v[76:77]

.LBB0_432:
	ds_read_b64_tr_b16 v[204:205], v203 offset:0x600
	ds_read_b64_tr_b16 v[206:207], v203 offset:0xe00
	ds_read_b64_tr_b16 v[208:209], v203 offset:0x1600
	ds_read_b64_tr_b16 v[210:211], v203 offset:0x1e00
	ds_read_b64_tr_b16 v[222:223], v203 offset:0x2600
	ds_read_b64_tr_b16 v[224:225], v203 offset:0x2e00
	ds_read_b64_tr_b16 v[226:227], v203 offset:0x3600
	ds_read_b64_tr_b16 v[228:229], v203 offset:0x3e00
	s_add_i32 s16, s18, 1
	s_cmp_lg_u32 s18, 2
	s_cselect_b32 s19, s16, 0
	s_waitcnt lgkmcnt(6)
	v_mfma_f32_32x32x16_bf16 v[16:31], v[88:91], v[204:207], v[16:31]
	s_lshl_b32 s16, s19, 14
	s_add_i32 s16, s16, 16
	s_waitcnt vmcnt(4)
	v_add_u32_e32 v88, s16, v184
	ds_write_b128 v88, v[144:147]
	v_cmp_gt_f32_e32 vcc, 1.0, v199
	s_waitcnt lgkmcnt(5)
	v_mfma_f32_32x32x16_bf16 v[16:31], v[92:95], v[208:211], v[16:31]
	s_waitcnt lgkmcnt(3)
	v_mfma_f32_32x32x16_bf16 v[16:31], v[80:83], v[222:225], v[16:31]
	v_add_u32_e32 v80, s16, v186
	ds_write_b128 v80, v[148:151]
	v_add_u32_e32 v80, s16, v183
	ds_write_b128 v80, v[152:155] offset:49152
	v_add_u32_e32 v80, s16, v188
	ds_write_b128 v80, v[156:159] offset:49152
	s_waitcnt lgkmcnt(4)
	v_mfma_f32_32x32x16_bf16 v[16:31], v[84:87], v[226:229], v[16:31]
	s_cbranch_vccz .LBB0_436
	s_and_saveexec_b64 s[16:17], s[0:1]
	ds_write_b32 v179, v199 offset:128
	s_or_b64 exec, exec, s[16:17]
	s_waitcnt lgkmcnt(0)
	v_add_u32_e32 v92, v177, v176
	ds_read_b128 v[80:83], v92 offset:224
	ds_read_b128 v[84:87], v92 offset:192
	ds_read_b128 v[88:91], v92 offset:160
	ds_read_b128 v[92:95], v92 offset:128
	s_waitcnt lgkmcnt(3)
	v_pk_mul_f32 v[12:13], v[12:13], v[80:81]
	s_waitcnt lgkmcnt(2)
	v_pk_mul_f32 v[8:9], v[8:9], v[84:85]
	s_waitcnt lgkmcnt(1)
	v_pk_mul_f32 v[4:5], v[4:5], v[88:89]
	v_pk_mul_f32 v[14:15], v[14:15], v[82:83]
	v_pk_mul_f32 v[10:11], v[10:11], v[86:87]
	v_pk_mul_f32 v[6:7], v[6:7], v[90:91]
	s_waitcnt lgkmcnt(0)
	v_pk_mul_f32 v[2:3], v[2:3], v[94:95]
	v_pk_mul_f32 v[0:1], v[0:1], v[92:93]
	v_pk_mul_f32 v[60:61], v[60:61], v[80:81]
	v_pk_mul_f32 v[56:57], v[56:57], v[84:85]
	v_pk_mul_f32 v[52:53], v[52:53], v[88:89]
	v_pk_mul_f32 v[62:63], v[62:63], v[82:83]
	v_pk_mul_f32 v[58:59], v[58:59], v[86:87]
	v_pk_mul_f32 v[54:55], v[54:55], v[90:91]
	v_pk_mul_f32 v[50:51], v[50:51], v[94:95]
	v_pk_mul_f32 v[48:49], v[48:49], v[92:93]
	v_pk_mul_f32 v[44:45], v[44:45], v[80:81]
	v_pk_mul_f32 v[40:41], v[40:41], v[84:85]
	v_pk_mul_f32 v[36:37], v[36:37], v[88:89]
	v_pk_mul_f32 v[46:47], v[46:47], v[82:83]
	v_pk_mul_f32 v[42:43], v[42:43], v[86:87]
	v_pk_mul_f32 v[38:39], v[38:39], v[90:91]
	v_pk_mul_f32 v[34:35], v[34:35], v[94:95]
	v_pk_mul_f32 v[32:33], v[32:33], v[92:93]
	v_pk_mul_f32 v[28:29], v[28:29], v[80:81]
	v_pk_mul_f32 v[24:25], v[24:25], v[84:85]
	v_pk_mul_f32 v[20:21], v[20:21], v[88:89]
	v_pk_mul_f32 v[30:31], v[30:31], v[82:83]
	v_pk_mul_f32 v[26:27], v[26:27], v[86:87]
	v_pk_mul_f32 v[22:23], v[22:23], v[90:91]
	v_pk_mul_f32 v[18:19], v[18:19], v[94:95]
	v_pk_mul_f32 v[16:17], v[16:17], v[92:93]
